# static s_setprio 1 for waves 4-7 during the GEMM phases only (raised at phase entry, dropped at the seam)
# speedup vs baseline: 1.0026x; 1.0026x over previous
.LBB0_166:
	v_readfirstlane_b32 vcc_lo, v216
	s_nop 3
	s_lshr_b32 vcc_lo, vcc_lo, 8
	s_cmp_eq_u32 vcc_lo, 1
	s_cbranch_scc0 .Lgprio_166
	s_setprio 1

.LBB0_185:
	s_setprio 0
	v_readlane_b32 s2, v246, 31
	s_add_i32 s5, s2, 2
	v_readlane_b32 s2, v250, 22
	v_readlane_b32 s3, v250, 23
	s_cmp_ge_i32 s5, s3
	s_cbranch_scc1 .LBB0_260
	v_readlane_b32 s6, v250, 56
	v_readlane_b32 s7, v250, 57
	s_mov_b64 s[2:3], -1
	s_and_b64 vcc, exec, s[6:7]
	s_cbranch_vccz .LBB0_240
	s_waitcnt vmcnt(0)
	s_barrier
	s_mov_b64 s[2:3], exec
	v_readlane_b32 s6, v250, 20
	v_readlane_b32 s7, v250, 21
	s_and_b64 s[6:7], s[2:3], s[6:7]
	s_mov_b64 exec, s[6:7]
	s_cbranch_execz .LBB0_239
	v_readlane_b32 s4, v246, 16
	s_waitcnt vmcnt(0) expcnt(0) lgkmcnt(0)
	s_nop 0
	v_mov_b32_e32 v0, s4
	ds_read_b32 v2, v0
	v_readlane_b32 s4, v246, 17
	s_waitcnt lgkmcnt(0)
	v_cmp_ne_u32_e32 vcc, 0, v2
	v_mov_b32_e32 v0, s4
	ds_read_b32 v0, v0
	s_cbranch_vccnz .LBB0_203
	s_mov_b32 s12, 1
	s_branch .LBB0_191

.LBB0_759:
.LBB0_760:
	v_readfirstlane_b32 vcc_lo, v216
	s_nop 3
	s_lshr_b32 vcc_lo, vcc_lo, 8
	s_cmp_eq_u32 vcc_lo, 1
	s_cbranch_scc0 .Lgprio_760
	s_setprio 1

.LBB0_799:
	s_setprio 0
	v_readlane_b32 s0, v246, 31
	s_add_i32 s5, s0, 6
	v_readlane_b32 s0, v250, 22
	v_readlane_b32 s1, v250, 23
	s_cmp_ge_i32 s5, s1
	s_cbranch_scc1 .LBB0_874
	v_readlane_b32 s2, v250, 56
	v_readlane_b32 s3, v250, 57
	s_mov_b64 s[0:1], -1
	s_and_b64 vcc, exec, s[2:3]
	s_cbranch_vccz .LBB0_854
	s_waitcnt vmcnt(0)
	s_waitcnt vmcnt(0) lgkmcnt(0)
	s_barrier
	s_mov_b64 s[0:1], exec
	v_readlane_b32 s2, v250, 20
	v_readlane_b32 s3, v250, 21
	s_and_b64 s[2:3], s[0:1], s[2:3]
	s_mov_b64 exec, s[2:3]
	s_cbranch_execz .LBB0_853
	v_readlane_b32 s2, v246, 16
	s_waitcnt vmcnt(0) expcnt(0) lgkmcnt(0)
	s_nop 0
	v_mov_b32_e32 v0, s2
	ds_read_b32 v2, v0
	v_readlane_b32 s2, v246, 17
	s_waitcnt lgkmcnt(0)
	v_cmp_ne_u32_e32 vcc, 0, v2
	v_mov_b32_e32 v0, s2
	ds_read_b32 v0, v0
	s_cbranch_vccnz .LBB0_817
	s_mov_b32 s10, 1
	s_branch .LBB0_805

.LBB0_897:
	s_setprio 0
	v_readlane_b32 s0, v246, 31
	s_add_i32 s5, s0, 7
	v_readlane_b32 s0, v250, 22
	v_readlane_b32 s1, v250, 23
	s_cmp_ge_i32 s5, s1
	s_cbranch_scc1 .LBB0_972
	v_readlane_b32 s2, v250, 56
	v_readlane_b32 s3, v250, 57
	s_mov_b64 s[0:1], -1
	s_and_b64 vcc, exec, s[2:3]
	s_cbranch_vccz .LBB0_952
	s_waitcnt vmcnt(0)
	s_waitcnt lgkmcnt(0)
	s_barrier
	s_mov_b64 s[0:1], exec
	v_readlane_b32 s2, v250, 20
	v_readlane_b32 s3, v250, 21
	s_and_b64 s[2:3], s[0:1], s[2:3]
	s_mov_b64 exec, s[2:3]
	s_cbranch_execz .LBB0_951
	v_readlane_b32 s2, v246, 16
	s_waitcnt vmcnt(0) expcnt(0) lgkmcnt(0)
	s_nop 0
	v_mov_b32_e32 v0, s2
	ds_read_b32 v2, v0
	v_readlane_b32 s2, v246, 17
	s_waitcnt lgkmcnt(0)
	v_cmp_ne_u32_e32 vcc, 0, v2
	v_mov_b32_e32 v0, s2
	ds_read_b32 v0, v0
	s_cbranch_vccnz .LBB0_915
	s_mov_b32 s10, 1
	s_branch .LBB0_903

.LBB0_1089:
	s_setprio 0
	v_readlane_b32 s0, v246, 31
	s_add_i32 s0, s0, 8
	s_cmp_ge_i32 s0, s5
	s_cbranch_scc1 .LBB0_165
	v_readlane_b32 s2, v250, 56
	v_readlane_b32 s3, v250, 57
	s_mov_b64 s[0:1], -1
	s_and_b64 vcc, exec, s[2:3]
	s_cbranch_vccz .LBB0_1144
	s_waitcnt vmcnt(0)
	s_waitcnt vmcnt(0) lgkmcnt(0)
	s_barrier
	s_mov_b64 s[0:1], exec
	v_readlane_b32 s2, v250, 20
	v_readlane_b32 s3, v250, 21
	s_and_b64 s[2:3], s[0:1], s[2:3]
	s_mov_b64 exec, s[2:3]
	s_cbranch_execz .LBB0_1143
	v_readlane_b32 s2, v246, 16
	s_waitcnt vmcnt(0) expcnt(0) lgkmcnt(0)
	s_nop 0
	v_mov_b32_e32 v0, s2
	ds_read_b32 v2, v0
	v_readlane_b32 s2, v246, 17
	s_waitcnt lgkmcnt(0)
	v_cmp_ne_u32_e32 vcc, 0, v2
	v_mov_b32_e32 v0, s2
	ds_read_b32 v0, v0
	s_cbranch_vccnz .LBB0_1107
	s_mov_b32 s5, 1
	s_branch .LBB0_1095
